# plus scan loaders: single park wait, value-row gather addresses derived by stride from the first row
# speedup vs baseline: 1.0110x; 1.0110x over previous
; #define LAS __attribute__((address_space(3)))
; __device__ __forceinline__ float bf1(bf16_t u) { return __uint_as_float(((unsigned)u) << 16); }
; __device__ __forceinline__ void scan_phase(const Params& P, int l, LAS unsigned char* lds) {
;     ...
;                         LAS unsigned char* sl = lds + (jw & 1) * SLOT + HGO;
; #pragma unroll
;                         for (int j = 0; j < 4; ++j) *(LAS u32x4*)(sl + (j * 64 + lane) * 16) = fq[j];
; #pragma unroll
;                         for (int m = 0; m < 8; ++m) *(LAS u32x2*)(sl + 4096 + (m * 64 + lane) * 8) = fk[m];
;                         *(LAS u32x2*)(sl + 8192 + lane * 8) = fa;
;                         if (lane < 32) *(LAS f32x4*)(sl + 8704 + lane * 16) = p15;
;                         *(LAS f32x4*)(sl + 9216 + lane * 16) = (f32x4){bf1(vr[0]), bf1(vr[1]), bf1(vr[2]), bf1(vr[3])};
.LBB0_681:
	s_mul_hi_u32 s14, s81, 0xaaaaaaab
	s_lshr_b32 s15, s14, 1
	s_mul_i32 s15, s15, 3
	s_sub_i32 s14, s27, s15
	s_add_i32 s14, s89, s14
	s_cmp_lg_u32 s14, -4
	s_cbranch_scc1 .LBB0_690
	s_cmp_lt_i32 s89, -1
	s_cselect_b64 s[20:21], -1, 0
	s_cmpk_eq_i32 s93, 0x1130
	s_cselect_b64 s[22:23], -1, 0
	s_or_b64 s[20:21], s[20:21], s[22:23]
	s_and_b64 vcc, exec, s[20:21]
	s_cbranch_vccnz .LBB0_686
	s_andn2_b32 s14, 1, s89
	s_mulk_i32 s14, 0x6500
	s_add_i32 s14, s14, 0
	v_add_u32_e32 v67, s14, v48
	v_add_u32_e32 v2, s14, v46
	v_add_u32_e32 v111, 0x100, v67
	s_waitcnt vmcnt(0)
	ds_write_b128 v2, v[16:19] offset:15616
	ds_write_b128 v2, v[12:15] offset:16640
	ds_write_b128 v2, v[8:11] offset:17664
	ds_write_b128 v2, v[4:7] offset:18688
	ds_write2st64_b64 v111, v[64:65], v[62:63] offset0:38 offset1:39
	ds_write2st64_b64 v111, v[60:61], v[42:43] offset0:40 offset1:41
	ds_write2st64_b64 v111, v[40:41], v[38:39] offset0:42 offset1:43
	ds_write2st64_b64 v111, v[36:37], v[34:35] offset0:44 offset1:45
	ds_write_b64 v67, v[0:1] offset:23808
	s_and_saveexec_b64 s[20:21], s[4:5]
	ds_write_b128 v2, v[20:23] offset:24320
	s_or_b64 exec, exec, s[20:21]
	v_lshlrev_b32_e32 v112, 16, v47
	v_lshlrev_b32_e32 v113, 16, v68
	v_lshlrev_b32_e32 v114, 16, v69
	v_lshlrev_b32_e32 v115, 16, v70
	ds_write_b128 v2, v[112:115] offset:24832

; __device__ __forceinline__ void scan_phase(const Params& P, int l, LAS unsigned char* lds) {
;     ...
; #pragma unroll
;                         for (int e = 0; e < 4; ++e) { const int s = 4 * quad + e; const int p = dir ? plo + TS - 1 - s : plo + s;
;                             vr[e] = H[(rowbase + p) * NPAD + C_HGI + h * 128 + col0 + col]; }
;                     }
.LBB0_689:
	s_or_b64 exec, exec, s[20:21]
	s_cmp_lt_i32 s89, 12
	s_cselect_b32 s14, 0xf0, s12
	s_add_i32 s14, s14, s92
	s_and_b64 s[20:21], s[8:9], exec
	s_cselect_b32 s14, s93, s14
	s_or_b32 s14, s14, 15
	v_sub_u32_e32 v2, s14, v45
	v_add_u32_e32 v67, s93, v45
	s_waitcnt vmcnt(15)
	v_cndmask_b32_e64 v68, v2, v67, s[8:9]
	s_waitcnt vmcnt(14)
	v_ashrrev_i32_e32 v69, 31, v68
	v_lshl_add_u64 v[68:69], s[16:17], 0, v[68:69]
	v_mad_u64_u32 v[112:113], s[20:21], v68, s43, v[24:25]
	v_mov_b32_e32 v2, v113
	v_mad_u64_u32 v[68:69], s[20:21], v69, s43, v[2:3]
	v_mov_b32_e32 v113, v68
	global_load_ushort v47, v[112:113], off
	s_and_b64 s[20:21], s[8:9], exec
	s_mov_b32 s20, 0xffff7600
	s_cselect_b32 s20, 0x8a00, s20
	s_cselect_b32 s21, 0, -1
	v_lshl_add_u64 v[112:113], v[112:113], 0, s[20:21]
	global_load_ushort v68, v[112:113], off
	v_lshl_add_u64 v[112:113], v[112:113], 0, s[20:21]
	global_load_ushort v69, v[112:113], off
	v_lshl_add_u64 v[112:113], v[112:113], 0, s[20:21]
	global_load_ushort v70, v[112:113], off

; #define LAS __attribute__((address_space(3)))
; __device__ __forceinline__ void scan_phase(const Params& P, int l, LAS unsigned char* lds) {
;     ...
;                         LAS unsigned char* sl = lds + (jw & 1) * SLOT;
; #pragma unroll
;                         for (int j = 0; j < 4; ++j) { *(LAS u32x4*)(sl + (j * 64 + lane) * 16) = fw[j]; *(LAS u32x4*)(sl + 4096 + (j * 64 + lane) * 16) = fq[j]; }
; #pragma unroll
;                         for (int m = 0; m < 8; ++m) *(LAS u32x2*)(sl + 8192 + (m * 64 + lane) * 8) = fk[m];
;                         *(LAS u32x2*)(sl + 12288 + lane * 8) = fa; *(LAS u32x2*)(sl + 12800 + lane * 8) = ft;
;                         *(LAS f32x4*)(sl + 13312 + lane * 16) = b4; *(LAS f32x4*)(sl + 14336 + lane * 16) = v4;
;                         if (lane == 0) *(LAS float*)(sl + 15360) = egC;
;                     }
;                     if (jl < NT) {
;                         const int n0 = jl * TS; const int plo = dir ? (n0 < 256 ? 256 - TS - n0 : TPB + 256 - TS - n0) : n0;
;                         const size_t task = (size_t)grp * NCHUNK + jl;
;                         const unsigned char* c1 = ws + WS_CP1 + task * CP1_STRIDE; const unsigned char* ck = ws + WS_CPK + task * 4096; const unsigned char* c2 = ws + WS_CP2 + task * CP2_STRIDE;
; #pragma unroll
;                         for (int j = 0; j < 4; ++j) { fw[j] = *(const u32x4*)(c1 + (size_t)(j * 64 + lane) * 16); fq[j] = *(const u32x4*)(c1 + 4096 + (size_t)(j * 64 + lane) * 16); }
; #pragma unroll
;                         for (int m = 0; m < 8; ++m) fk[m] = *(const u32x2*)(ck + (size_t)(m * 64 + lane) * 8);
;                         fa = *(const u32x2*)(c2 + (size_t)lane * 8); ft = *(const u32x2*)(c2 + 512 + (size_t)lane * 8);
;                         b4 = *(const f32x4*)(c2 + 1024 + quad * 16); egC = *(const float*)(c2 + 1024 + 64);
; #pragma unroll
;                         for (int e = 0; e < 4; ++e) { const int s = 4 * quad + e; const int p = dir ? plo + TS - 1 - s : plo + s;
;                             v4[e] = DNV[(rowbase + p) * 1024 + h * 128 + col0 + col]; }
.LBB0_733:
	s_mul_hi_u32 s14, s73, 0xaaaaaaab
	s_lshr_b32 s14, s14, 1
	s_mul_i32 s14, s14, 3
	s_sub_i32 s15, s88, s14
	s_add_i32 s15, s82, s15
	s_cmp_lg_u32 s15, -4
	s_cbranch_scc1 .LBB0_740
	s_cmp_lt_i32 s82, -1
	s_cselect_b64 s[20:21], -1, 0
	s_cmpk_eq_i32 s89, 0x1130
	s_cselect_b64 s[22:23], -1, 0
	s_or_b64 s[20:21], s[20:21], s[22:23]
	s_and_b64 vcc, exec, s[20:21]
	s_cbranch_vccnz .LBB0_738
	s_andn2_b32 s15, 1, s82
	s_mulk_i32 s15, 0x6500
	s_add_i32 s15, s15, 0
	v_add_u32_e32 v0, s15, v46
	v_add_u32_e32 v1, s15, v48
	s_waitcnt vmcnt(0)
	ds_write_b128 v0, v[4:7]
	ds_write_b128 v0, v[12:15] offset:4096
	ds_write_b128 v0, v[16:19] offset:1024
	ds_write_b128 v0, v[24:27] offset:5120
	ds_write_b128 v0, v[20:23] offset:2048
	ds_write_b128 v0, v[28:31] offset:6144
	ds_write_b128 v0, v[8:11] offset:3072
	ds_write_b128 v0, v[32:35] offset:7168
	ds_write2st64_b64 v1, v[84:85], v[82:83] offset0:16 offset1:17
	ds_write2st64_b64 v1, v[80:81], v[78:79] offset0:18 offset1:19
	ds_write2st64_b64 v1, v[76:77], v[74:75] offset0:20 offset1:21
	ds_write2st64_b64 v1, v[72:73], v[70:71] offset0:22 offset1:23
	ds_write2st64_b64 v1, v[86:87], v[88:89] offset0:24 offset1:25
	ds_write_b128 v0, v[36:39] offset:13312
	ds_write_b128 v0, v[40:43] offset:14336
	s_and_saveexec_b64 s[20:21], s[6:7]
	v_mov_b32_e32 v0, s15
	ds_write_b32 v0, v47 offset:15360
	s_or_b64 exec, exec, s[20:21]
.LBB0_738:
	s_cmpk_gt_i32 s82, 0x10b
	s_cbranch_scc1 .LBB0_740
	v_readlane_b32 s22, v252, 2
	v_readlane_b32 s23, v252, 3
	s_cmp_lt_i32 s82, 12
	s_cselect_b32 s15, 0xf0, s93
	v_lshl_add_u64 v[0:1], s[22:23], 0, v[68:69]
	s_waitcnt vmcnt(17)
	v_add_co_u32_e32 v8, vcc, 0x38b60000, v0
	s_add_i32 s15, s15, s83
	s_nop 0
	v_addc_co_u32_e32 v9, vcc, 0, v1, vcc
	v_add_co_u32_e32 v0, vcc, 0x38b61000, v0
	global_load_dwordx4 v[4:7], v[8:9], off
	s_nop 0
	v_addc_co_u32_e32 v1, vcc, 0, v1, vcc
	global_load_dwordx4 v[12:15], v[0:1], off
	global_load_dwordx4 v[16:19], v[8:9], off offset:1024
	global_load_dwordx4 v[24:27], v[0:1], off offset:1024
	global_load_dwordx4 v[20:23], v[8:9], off offset:2048
	global_load_dwordx4 v[28:31], v[0:1], off offset:2048
	s_nop 0
	global_load_dwordx4 v[8:11], v[8:9], off offset:3072
	s_nop 0
	global_load_dwordx4 v[32:35], v[0:1], off offset:3072
	v_lshl_add_u64 v[0:1], s[22:23], 0, v[66:67]
	v_add_co_u32_e32 v0, vcc, 0x17600000, v0
	s_and_b64 s[20:21], s[8:9], exec
	s_nop 0
	v_addc_co_u32_e32 v1, vcc, 0, v1, vcc
	global_load_dwordx2 v[84:85], v[0:1], off
	global_load_dwordx2 v[82:83], v[0:1], off offset:512
	global_load_dwordx2 v[80:81], v[0:1], off offset:1024
	global_load_dwordx2 v[78:79], v[0:1], off offset:1536
	global_load_dwordx2 v[76:77], v[0:1], off offset:2048
	global_load_dwordx2 v[74:75], v[0:1], off offset:2560
	global_load_dwordx2 v[72:73], v[0:1], off offset:3072
	global_load_dwordx2 v[70:71], v[0:1], off offset:3584
	v_lshl_add_u64 v[0:1], s[22:23], 0, v[64:65]
	s_mov_b32 s20, 0x413d0000
	v_add_co_u32_e32 v0, vcc, s20, v0
	s_cselect_b32 s15, s89, s15
	s_nop 0
	v_addc_co_u32_e32 v1, vcc, 0, v1, vcc
	s_add_u32 s20, s22, s80
	global_load_dwordx2 v[86:87], v[0:1], off
	global_load_dwordx2 v[88:89], v[0:1], off offset:512
	v_lshl_add_u64 v[0:1], s[22:23], 0, v[62:63]
	s_addc_u32 s21, s23, s81
	s_or_b32 s15, s15, 15
	global_load_dwordx4 v[36:39], v[0:1], off
	global_load_dword v47, v3, s[20:21]
	v_sub_u32_e32 v0, s15, v45
	v_add_u32_e32 v2, s89, v45
	v_cndmask_b32_e64 v0, v0, v2, s[8:9]
	v_ashrrev_i32_e32 v1, 31, v0
	v_lshl_add_u64 v[0:1], s[16:17], 0, v[0:1]
	v_lshlrev_b64 v[0:1], 12, v[0:1]
	v_lshl_add_u64 v[0:1], v[60:61], 0, v[0:1]
	global_load_dword v40, v[0:1], off
	s_and_b64 s[20:21], s[8:9], exec
	s_mov_b32 s20, 0xfffff000
	s_cselect_b32 s20, 0x1000, s20
	s_cselect_b32 s21, 0, -1
	v_lshl_add_u64 v[0:1], v[0:1], 0, s[20:21]
	global_load_dword v41, v[0:1], off
	v_lshl_add_u64 v[0:1], v[0:1], 0, s[20:21]
	global_load_dword v42, v[0:1], off
	v_lshl_add_u64 v[0:1], v[0:1], 0, s[20:21]
	global_load_dword v43, v[0:1], off
